# fast chunk path: row-sum add chain interleaved with the exp/cvt instructions
# speedup vs baseline: 1.0050x; 1.0050x over previous
; #define MFMA16(a, b, c) __builtin_amdgcn_mfma_f32_16x16x32_bf16((a), (b), (c), 0, 0, 0)
; DI unsigned pk2(float lo, float hi) { f32x2 v = {lo, hi}; bf16x2_t b = __builtin_convertvector(v, bf16x2_t); return __builtin_bit_cast(unsigned, b); }
; template <int MODE>
; DI void nsa_chunk(const KVFrag& f, int kb, int t, bool selbit, const bf16x8 (&qf)[4][2], f32x4 (&O)[4][4], float (&m)[4], float (&l)[4], int quad, bool online) {
;     ...
;     float pv[8]; float ps = 0.f;
; #pragma unroll
;     for (int idx = 0; idx < 8; ++idx) { pv[idx] = val[idx] ? __builtin_amdgcn_exp2f(fmaf(s[idx >> 2][idx & 3], SC, -mn)) : 0.f; ps += pv[idx]; }
;     l[hh] += ps;
;     const bf16x8 pf = mk8((u32x4){pk2(pv[0], pv[1]), pk2(pv[2], pv[3]), pk2(pv[4], pv[5]), pk2(pv[6], pv[7])});
; #pragma unroll
;     for (int dt = 0; dt < 4; ++dt) O[hh][dt] = MFMA16(f.v[dt], pf, O[hh][dt]);
;   }
.Lmy_fast_s1:
	s_waitcnt lgkmcnt(4)
	v_mfma_f32_16x16x32_bf16 v[182:185], v[136:139], v[8:11], v[218:221]
	v_mfma_f32_16x16x32_bf16 v[182:185], v[140:143], v[12:15], v[182:185]
	v_mfma_f32_16x16x32_bf16 v[186:189], v[144:147], v[8:11], v[222:225]
	v_mfma_f32_16x16x32_bf16 v[186:189], v[132:135], v[12:15], v[186:189]
	v_mfma_f32_16x16x32_bf16 v[190:193], v[136:139], v[16:19], v[218:221]
	v_mfma_f32_16x16x32_bf16 v[190:193], v[140:143], v[20:23], v[190:193]
	v_mfma_f32_16x16x32_bf16 v[194:197], v[144:147], v[16:19], v[222:225]
	v_mfma_f32_16x16x32_bf16 v[194:197], v[132:135], v[20:23], v[194:197]
	s_waitcnt lgkmcnt(0)
	s_nop 2
	v_pk_fma_f32 v[240:241], v[182:183], s[34:35], v[2:3] op_sel:[0,0,1] op_sel_hi:[1,0,1] neg_lo:[0,0,1] neg_hi:[0,0,1]
	v_pk_fma_f32 v[242:243], v[184:185], s[34:35], v[2:3] op_sel:[0,0,1] op_sel_hi:[1,0,1] neg_lo:[0,0,1] neg_hi:[0,0,1]
	v_pk_fma_f32 v[244:245], v[186:187], s[34:35], v[2:3] op_sel:[0,0,1] op_sel_hi:[1,0,1] neg_lo:[0,0,1] neg_hi:[0,0,1]
	v_pk_fma_f32 v[246:247], v[188:189], s[34:35], v[2:3] op_sel:[0,0,1] op_sel_hi:[1,0,1] neg_lo:[0,0,1] neg_hi:[0,0,1]
	v_exp_f32_e32 v240, v240
	v_exp_f32_e32 v241, v241
	v_mfma_f32_16x16x32_bf16 v[182:185], v[136:139], v[24:27], v[218:221]
	v_exp_f32_e32 v242, v242
	v_add_f32_e32 v205, 0, v240
	v_mfma_f32_16x16x32_bf16 v[182:185], v[140:143], v[28:31], v[182:185]
	v_exp_f32_e32 v243, v243
	v_add_f32_e32 v205, v241, v205
	v_mfma_f32_16x16x32_bf16 v[186:189], v[144:147], v[24:27], v[222:225]
	v_exp_f32_e32 v244, v244
	v_add_f32_e32 v205, v242, v205
	v_mfma_f32_16x16x32_bf16 v[186:189], v[132:135], v[28:31], v[186:189]
	v_exp_f32_e32 v245, v245
	v_add_f32_e32 v205, v243, v205
	v_exp_f32_e32 v246, v246
	v_add_f32_e32 v205, v244, v205
	v_exp_f32_e32 v247, v247
	v_add_f32_e32 v205, v245, v205
	v_cvt_pk_bf16_f32 v248, v240, v241
	v_add_f32_e32 v205, v246, v205
	v_cvt_pk_bf16_f32 v249, v242, v243
	v_cvt_pk_bf16_f32 v250, v244, v245
	v_add_f32_e32 v205, v247, v205
	v_cvt_pk_bf16_f32 v251, v246, v247
	v_add_f32_e32 v167, v167, v205
	v_pk_fma_f32 v[240:241], v[190:191], s[34:35], v[2:3] op_sel_hi:[1,0,0] neg_lo:[0,0,1] neg_hi:[0,0,1]
	v_pk_fma_f32 v[242:243], v[192:193], s[34:35], v[2:3] op_sel_hi:[1,0,0] neg_lo:[0,0,1] neg_hi:[0,0,1]
	v_pk_fma_f32 v[244:245], v[194:195], s[34:35], v[2:3] op_sel_hi:[1,0,0] neg_lo:[0,0,1] neg_hi:[0,0,1]
	v_pk_fma_f32 v[246:247], v[196:197], s[34:35], v[2:3] op_sel_hi:[1,0,0] neg_lo:[0,0,1] neg_hi:[0,0,1]
	v_exp_f32_e32 v240, v240
	v_exp_f32_e32 v241, v241
	v_mfma_f32_16x16x32_bf16 v[190:193], v[136:139], v[32:35], v[218:221]
	v_exp_f32_e32 v242, v242
	v_add_f32_e32 v205, 0, v240
	v_mfma_f32_16x16x32_bf16 v[190:193], v[140:143], v[36:39], v[190:193]
	v_exp_f32_e32 v243, v243
	v_add_f32_e32 v205, v241, v205
	v_mfma_f32_16x16x32_bf16 v[194:197], v[144:147], v[32:35], v[222:225]
	v_exp_f32_e32 v244, v244
	v_add_f32_e32 v205, v242, v205
	v_mfma_f32_16x16x32_bf16 v[194:197], v[132:135], v[36:39], v[194:197]
	v_exp_f32_e32 v245, v245
	v_add_f32_e32 v205, v243, v205
	v_mfma_f32_16x16x32_bf16 v[104:107], v[128:131], v[248:251], v[104:107]
	v_exp_f32_e32 v246, v246
	v_add_f32_e32 v205, v244, v205
	v_mfma_f32_16x16x32_bf16 v[100:103], v[124:127], v[248:251], v[100:103]
	v_exp_f32_e32 v247, v247
	v_add_f32_e32 v205, v245, v205
	v_mfma_f32_16x16x32_bf16 v[96:99], v[120:123], v[248:251], v[96:99]
	v_cvt_pk_bf16_f32 v198, v240, v241
	v_add_f32_e32 v205, v246, v205
	v_mfma_f32_16x16x32_bf16 v[92:95], v[116:119], v[248:251], v[92:95]
	v_cvt_pk_bf16_f32 v199, v242, v243
	v_cvt_pk_bf16_f32 v200, v244, v245
	v_add_f32_e32 v205, v247, v205
	v_cvt_pk_bf16_f32 v201, v246, v247
	v_add_f32_e32 v166, v166, v205
	v_pk_fma_f32 v[240:241], v[182:183], s[34:35], v[0:1] op_sel_hi:[1,0,0] neg_lo:[0,0,1] neg_hi:[0,0,1]
	v_pk_fma_f32 v[242:243], v[184:185], s[34:35], v[0:1] op_sel_hi:[1,0,0] neg_lo:[0,0,1] neg_hi:[0,0,1]
	v_pk_fma_f32 v[244:245], v[186:187], s[34:35], v[0:1] op_sel_hi:[1,0,0] neg_lo:[0,0,1] neg_hi:[0,0,1]
	v_pk_fma_f32 v[246:247], v[188:189], s[34:35], v[0:1] op_sel_hi:[1,0,0] neg_lo:[0,0,1] neg_hi:[0,0,1]
	v_exp_f32_e32 v240, v240
	v_exp_f32_e32 v241, v241
	v_mfma_f32_16x16x32_bf16 v[88:91], v[128:131], v[198:201], v[88:91]
	v_exp_f32_e32 v242, v242
	v_add_f32_e32 v205, 0, v240
	v_mfma_f32_16x16x32_bf16 v[84:87], v[124:127], v[198:201], v[84:87]
	v_exp_f32_e32 v243, v243
	v_add_f32_e32 v205, v241, v205
	v_mfma_f32_16x16x32_bf16 v[80:83], v[120:123], v[198:201], v[80:83]
	v_exp_f32_e32 v244, v244
	v_add_f32_e32 v205, v242, v205
	v_mfma_f32_16x16x32_bf16 v[76:79], v[116:119], v[198:201], v[76:79]
	v_exp_f32_e32 v245, v245
	v_add_f32_e32 v205, v243, v205
	v_exp_f32_e32 v246, v246
	v_add_f32_e32 v205, v244, v205
	v_exp_f32_e32 v247, v247
	v_add_f32_e32 v205, v245, v205
	v_cvt_pk_bf16_f32 v248, v240, v241
	v_add_f32_e32 v205, v246, v205
	v_cvt_pk_bf16_f32 v249, v242, v243
	v_cvt_pk_bf16_f32 v250, v244, v245
	v_add_f32_e32 v205, v247, v205
	v_cvt_pk_bf16_f32 v251, v246, v247
	v_add_f32_e32 v165, v165, v205
	v_pk_fma_f32 v[240:241], v[190:191], s[34:35], v[180:181] op_sel_hi:[1,0,0] neg_lo:[0,0,1] neg_hi:[0,0,1]
	v_pk_fma_f32 v[242:243], v[192:193], s[34:35], v[180:181] op_sel_hi:[1,0,0] neg_lo:[0,0,1] neg_hi:[0,0,1]
	v_pk_fma_f32 v[244:245], v[194:195], s[34:35], v[180:181] op_sel_hi:[1,0,0] neg_lo:[0,0,1] neg_hi:[0,0,1]
	v_pk_fma_f32 v[246:247], v[196:197], s[34:35], v[180:181] op_sel_hi:[1,0,0] neg_lo:[0,0,1] neg_hi:[0,0,1]
	v_exp_f32_e32 v240, v240
	v_exp_f32_e32 v241, v241
	v_mfma_f32_16x16x32_bf16 v[72:75], v[128:131], v[248:251], v[72:75]
	v_exp_f32_e32 v242, v242
	v_add_f32_e32 v205, 0, v240
	v_mfma_f32_16x16x32_bf16 v[68:71], v[124:127], v[248:251], v[68:71]
	v_exp_f32_e32 v243, v243
	v_add_f32_e32 v205, v241, v205
	v_mfma_f32_16x16x32_bf16 v[64:67], v[120:123], v[248:251], v[64:67]
	v_exp_f32_e32 v244, v244
	v_add_f32_e32 v205, v242, v205
	v_mfma_f32_16x16x32_bf16 v[60:63], v[116:119], v[248:251], v[60:63]
	v_exp_f32_e32 v245, v245
	v_add_f32_e32 v205, v243, v205
	v_exp_f32_e32 v246, v246
	v_add_f32_e32 v205, v244, v205
	v_exp_f32_e32 v247, v247
	v_add_f32_e32 v205, v245, v205
	v_cvt_pk_bf16_f32 v198, v240, v241
	v_add_f32_e32 v205, v246, v205
	v_cvt_pk_bf16_f32 v199, v242, v243
	v_cvt_pk_bf16_f32 v200, v244, v245
	v_add_f32_e32 v205, v247, v205
	v_cvt_pk_bf16_f32 v201, v246, v247
	v_add_f32_e32 v164, v164, v205
	s_nop 0
	v_mfma_f32_16x16x32_bf16 v[56:59], v[128:131], v[198:201], v[56:59]
	v_mfma_f32_16x16x32_bf16 v[52:55], v[124:127], v[198:201], v[52:55]
	v_mfma_f32_16x16x32_bf16 v[48:51], v[120:123], v[198:201], v[48:51]
	v_mfma_f32_16x16x32_bf16 v[44:47], v[116:119], v[198:201], v[44:47]
	s_branch .LBB0_737
; #define MFMA16(a, b, c) __builtin_amdgcn_mfma_f32_16x16x32_bf16((a), (b), (c), 0, 0, 0)
; DI unsigned pk2(float lo, float hi) { f32x2 v = {lo, hi}; bf16x2_t b = __builtin_convertvector(v, bf16x2_t); return __builtin_bit_cast(unsigned, b); }
; template <int MODE>
; DI void nsa_chunk(const KVFrag& f, int kb, int t, bool selbit, const bf16x8 (&qf)[4][2], f32x4 (&O)[4][4], float (&m)[4], float (&l)[4], int quad, bool online) {
;     ...
;   for (int hh = 0; hh < 4; ++hh) {
;     f32x4 s[2];
; #pragma unroll
;     for (int a = 0; a < 2; ++a) { s[a] = MFMA16(f.k[a][0], qf[hh][0], ((f32x4){0.f, 0.f, 0.f, 0.f})); s[a] = MFMA16(f.k[a][1], qf[hh][1], s[a]); }
;     float mn = m[hh];
;     if (online) {
;       float cm = -1e30f;
; #pragma unroll
;       for (int idx = 0; idx < 8; ++idx) if (val[idx]) cm = fmaxf(cm, s[idx >> 2][idx & 3] * SC);
;       cm = fmaxf(cm, __shfl_xor(cm, 16)); cm = fmaxf(cm, __shfl_xor(cm, 32));
;       mn = fmaxf(mn, cm);
;       const float alpha = __builtin_amdgcn_exp2f(m[hh] - mn);
;       m[hh] = mn; l[hh] *= alpha;
; #pragma unroll
;       for (int dt = 0; dt < 4; ++dt) O[hh][dt] = O[hh][dt] * alpha;
;     }
;     float pv[8]; float ps = 0.f;
; #pragma unroll
;     for (int idx = 0; idx < 8; ++idx) { pv[idx] = val[idx] ? __builtin_amdgcn_exp2f(fmaf(s[idx >> 2][idx & 3], SC, -mn)) : 0.f; ps += pv[idx]; }
;     l[hh] += ps;
;     const bf16x8 pf = mk8((u32x4){pk2(pv[0], pv[1]), pk2(pv[2], pv[3]), pk2(pv[4], pv[5]), pk2(pv[6], pv[7])});
; #pragma unroll
;     for (int dt = 0; dt < 4; ++dt) O[hh][dt] = MFMA16(f.v[dt], pf, O[hh][dt]);
;   }
.Lmy_full_s1:
	s_waitcnt lgkmcnt(4)
	v_mfma_f32_16x16x32_bf16 v[182:185], v[136:139], v[8:11], v[218:221]
	v_mfma_f32_16x16x32_bf16 v[182:185], v[140:143], v[12:15], v[182:185]
	v_mfma_f32_16x16x32_bf16 v[186:189], v[144:147], v[8:11], v[218:221]
	v_mfma_f32_16x16x32_bf16 v[186:189], v[132:135], v[12:15], v[186:189]
	v_mfma_f32_16x16x32_bf16 v[190:193], v[136:139], v[16:19], v[218:221]
	v_mfma_f32_16x16x32_bf16 v[190:193], v[140:143], v[20:23], v[190:193]
	v_mfma_f32_16x16x32_bf16 v[194:197], v[144:147], v[16:19], v[218:221]
	v_mfma_f32_16x16x32_bf16 v[194:197], v[132:135], v[20:23], v[194:197]
	s_waitcnt lgkmcnt(0)
	s_nop 2
	v_pk_fma_f32 v[240:241], v[182:183], s[34:35], v[2:3] op_sel:[0,0,1] op_sel_hi:[1,0,1] neg_lo:[0,0,1] neg_hi:[0,0,1]
	v_pk_fma_f32 v[242:243], v[184:185], s[34:35], v[2:3] op_sel:[0,0,1] op_sel_hi:[1,0,1] neg_lo:[0,0,1] neg_hi:[0,0,1]
	v_pk_fma_f32 v[244:245], v[186:187], s[34:35], v[2:3] op_sel:[0,0,1] op_sel_hi:[1,0,1] neg_lo:[0,0,1] neg_hi:[0,0,1]
	v_pk_fma_f32 v[246:247], v[188:189], s[34:35], v[2:3] op_sel:[0,0,1] op_sel_hi:[1,0,1] neg_lo:[0,0,1] neg_hi:[0,0,1]
	v_exp_f32_e32 v240, v240
	v_exp_f32_e32 v241, v241
	v_mfma_f32_16x16x32_bf16 v[182:185], v[136:139], v[24:27], v[218:221]
	v_exp_f32_e32 v242, v242
	v_add_f32_e32 v205, 0, v240
	v_mfma_f32_16x16x32_bf16 v[182:185], v[140:143], v[28:31], v[182:185]
	v_exp_f32_e32 v243, v243
	v_add_f32_e32 v205, v241, v205
	v_mfma_f32_16x16x32_bf16 v[186:189], v[144:147], v[24:27], v[218:221]
	v_exp_f32_e32 v244, v244
	v_add_f32_e32 v205, v242, v205
	v_mfma_f32_16x16x32_bf16 v[186:189], v[132:135], v[28:31], v[186:189]
	v_exp_f32_e32 v245, v245
	v_add_f32_e32 v205, v243, v205
	v_exp_f32_e32 v246, v246
	v_add_f32_e32 v205, v244, v205
	v_exp_f32_e32 v247, v247
	v_add_f32_e32 v205, v245, v205
	v_cvt_pk_bf16_f32 v248, v240, v241
	v_add_f32_e32 v205, v246, v205
	v_cvt_pk_bf16_f32 v249, v242, v243
	v_cvt_pk_bf16_f32 v250, v244, v245
	v_add_f32_e32 v205, v247, v205
	v_cvt_pk_bf16_f32 v251, v246, v247
	v_add_f32_e32 v167, v167, v205
	v_pk_fma_f32 v[240:241], v[190:191], s[34:35], v[2:3] op_sel_hi:[1,0,0] neg_lo:[0,0,1] neg_hi:[0,0,1]
	v_pk_fma_f32 v[242:243], v[192:193], s[34:35], v[2:3] op_sel_hi:[1,0,0] neg_lo:[0,0,1] neg_hi:[0,0,1]
	v_pk_fma_f32 v[244:245], v[194:195], s[34:35], v[2:3] op_sel_hi:[1,0,0] neg_lo:[0,0,1] neg_hi:[0,0,1]
	v_pk_fma_f32 v[246:247], v[196:197], s[34:35], v[2:3] op_sel_hi:[1,0,0] neg_lo:[0,0,1] neg_hi:[0,0,1]
	v_exp_f32_e32 v240, v240
	v_exp_f32_e32 v241, v241
	v_mfma_f32_16x16x32_bf16 v[190:193], v[136:139], v[32:35], v[218:221]
	v_exp_f32_e32 v242, v242
	v_add_f32_e32 v205, 0, v240
	v_mfma_f32_16x16x32_bf16 v[190:193], v[140:143], v[36:39], v[190:193]
	v_exp_f32_e32 v243, v243
	v_add_f32_e32 v205, v241, v205
	v_mfma_f32_16x16x32_bf16 v[194:197], v[144:147], v[32:35], v[218:221]
	v_exp_f32_e32 v244, v244
	v_add_f32_e32 v205, v242, v205
	v_mfma_f32_16x16x32_bf16 v[194:197], v[132:135], v[36:39], v[194:197]
	v_exp_f32_e32 v245, v245
	v_add_f32_e32 v205, v243, v205
	v_mfma_f32_16x16x32_bf16 v[104:107], v[128:131], v[248:251], v[104:107]
	v_exp_f32_e32 v246, v246
	v_add_f32_e32 v205, v244, v205
	v_mfma_f32_16x16x32_bf16 v[100:103], v[124:127], v[248:251], v[100:103]
	v_exp_f32_e32 v247, v247
	v_add_f32_e32 v205, v245, v205
	v_mfma_f32_16x16x32_bf16 v[96:99], v[120:123], v[248:251], v[96:99]
	v_cvt_pk_bf16_f32 v198, v240, v241
	v_add_f32_e32 v205, v246, v205
	v_mfma_f32_16x16x32_bf16 v[92:95], v[116:119], v[248:251], v[92:95]
	v_cvt_pk_bf16_f32 v199, v242, v243
	v_cvt_pk_bf16_f32 v200, v244, v245
	v_add_f32_e32 v205, v247, v205
	v_cvt_pk_bf16_f32 v201, v246, v247
	v_add_f32_e32 v166, v166, v205
	v_pk_fma_f32 v[240:241], v[182:183], s[34:35], v[0:1] op_sel_hi:[1,0,0] neg_lo:[0,0,1] neg_hi:[0,0,1]
	v_pk_fma_f32 v[242:243], v[184:185], s[34:35], v[0:1] op_sel_hi:[1,0,0] neg_lo:[0,0,1] neg_hi:[0,0,1]
	v_pk_fma_f32 v[244:245], v[186:187], s[34:35], v[0:1] op_sel_hi:[1,0,0] neg_lo:[0,0,1] neg_hi:[0,0,1]
	v_pk_fma_f32 v[246:247], v[188:189], s[34:35], v[0:1] op_sel_hi:[1,0,0] neg_lo:[0,0,1] neg_hi:[0,0,1]
	v_exp_f32_e32 v240, v240
	v_exp_f32_e32 v241, v241
	v_mfma_f32_16x16x32_bf16 v[88:91], v[128:131], v[198:201], v[88:91]
	v_exp_f32_e32 v242, v242
	v_add_f32_e32 v205, 0, v240
	v_mfma_f32_16x16x32_bf16 v[84:87], v[124:127], v[198:201], v[84:87]
	v_exp_f32_e32 v243, v243
	v_add_f32_e32 v205, v241, v205
	v_mfma_f32_16x16x32_bf16 v[80:83], v[120:123], v[198:201], v[80:83]
	v_exp_f32_e32 v244, v244
	v_add_f32_e32 v205, v242, v205
	v_mfma_f32_16x16x32_bf16 v[76:79], v[116:119], v[198:201], v[76:79]
	v_exp_f32_e32 v245, v245
	v_add_f32_e32 v205, v243, v205
	v_exp_f32_e32 v246, v246
	v_add_f32_e32 v205, v244, v205
	v_exp_f32_e32 v247, v247
	v_add_f32_e32 v205, v245, v205
	v_cvt_pk_bf16_f32 v248, v240, v241
	v_add_f32_e32 v205, v246, v205
	v_cvt_pk_bf16_f32 v249, v242, v243
	v_cvt_pk_bf16_f32 v250, v244, v245
	v_add_f32_e32 v205, v247, v205
	v_cvt_pk_bf16_f32 v251, v246, v247
	v_add_f32_e32 v165, v165, v205
	v_pk_fma_f32 v[240:241], v[190:191], s[34:35], v[180:181] op_sel_hi:[1,0,0] neg_lo:[0,0,1] neg_hi:[0,0,1]
	v_pk_fma_f32 v[242:243], v[192:193], s[34:35], v[180:181] op_sel_hi:[1,0,0] neg_lo:[0,0,1] neg_hi:[0,0,1]
	v_pk_fma_f32 v[244:245], v[194:195], s[34:35], v[180:181] op_sel_hi:[1,0,0] neg_lo:[0,0,1] neg_hi:[0,0,1]
	v_pk_fma_f32 v[246:247], v[196:197], s[34:35], v[180:181] op_sel_hi:[1,0,0] neg_lo:[0,0,1] neg_hi:[0,0,1]
	v_exp_f32_e32 v240, v240
	v_exp_f32_e32 v241, v241
	v_mfma_f32_16x16x32_bf16 v[72:75], v[128:131], v[248:251], v[72:75]
	v_exp_f32_e32 v242, v242
	v_add_f32_e32 v205, 0, v240
	v_mfma_f32_16x16x32_bf16 v[68:71], v[124:127], v[248:251], v[68:71]
	v_exp_f32_e32 v243, v243
	v_add_f32_e32 v205, v241, v205
	v_mfma_f32_16x16x32_bf16 v[64:67], v[120:123], v[248:251], v[64:67]
	v_exp_f32_e32 v244, v244
	v_add_f32_e32 v205, v242, v205
	v_mfma_f32_16x16x32_bf16 v[60:63], v[116:119], v[248:251], v[60:63]
	v_exp_f32_e32 v245, v245
	v_add_f32_e32 v205, v243, v205
	v_exp_f32_e32 v246, v246
	v_add_f32_e32 v205, v244, v205
	v_exp_f32_e32 v247, v247
	v_add_f32_e32 v205, v245, v205
	v_cvt_pk_bf16_f32 v198, v240, v241
	v_add_f32_e32 v205, v246, v205
	v_cvt_pk_bf16_f32 v199, v242, v243
	v_cvt_pk_bf16_f32 v200, v244, v245
	v_add_f32_e32 v205, v247, v205
	v_cvt_pk_bf16_f32 v201, v246, v247
	v_add_f32_e32 v164, v164, v205
	s_nop 0
	v_mfma_f32_16x16x32_bf16 v[56:59], v[128:131], v[198:201], v[56:59]
	v_mfma_f32_16x16x32_bf16 v[52:55], v[124:127], v[198:201], v[52:55]
	v_mfma_f32_16x16x32_bf16 v[48:51], v[120:123], v[198:201], v[48:51]
	v_mfma_f32_16x16x32_bf16 v[44:47], v[116:119], v[198:201], v[44:47]
	s_branch .LBB0_737

; #define MFMA16(a, b, c) __builtin_amdgcn_mfma_f32_16x16x32_bf16((a), (b), (c), 0, 0, 0)
; DI unsigned pk2(float lo, float hi) { f32x2 v = {lo, hi}; bf16x2_t b = __builtin_convertvector(v, bf16x2_t); return __builtin_bit_cast(unsigned, b); }
; template <int MODE>
; DI void nsa_chunk(const KVFrag& f, int kb, int t, bool selbit, const bf16x8 (&qf)[4][2], f32x4 (&O)[4][4], float (&m)[4], float (&l)[4], int quad, bool online) {
;     ...
;   for (int hh = 0; hh < 4; ++hh) {
;     f32x4 s[2];
; #pragma unroll
;     for (int a = 0; a < 2; ++a) { s[a] = MFMA16(f.k[a][0], qf[hh][0], ((f32x4){0.f, 0.f, 0.f, 0.f})); s[a] = MFMA16(f.k[a][1], qf[hh][1], s[a]); }
;     float mn = m[hh];
;     if (online) {
;       float cm = -1e30f;
; #pragma unroll
;       for (int idx = 0; idx < 8; ++idx) if (val[idx]) cm = fmaxf(cm, s[idx >> 2][idx & 3] * SC);
;       cm = fmaxf(cm, __shfl_xor(cm, 16)); cm = fmaxf(cm, __shfl_xor(cm, 32));
;       mn = fmaxf(mn, cm);
;       const float alpha = __builtin_amdgcn_exp2f(m[hh] - mn);
;       m[hh] = mn; l[hh] *= alpha;
; #pragma unroll
;       for (int dt = 0; dt < 4; ++dt) O[hh][dt] = O[hh][dt] * alpha;
;     }
;     float pv[8]; float ps = 0.f;
; #pragma unroll
;     for (int idx = 0; idx < 8; ++idx) { pv[idx] = val[idx] ? __builtin_amdgcn_exp2f(fmaf(s[idx >> 2][idx & 3], SC, -mn)) : 0.f; ps += pv[idx]; }
;     l[hh] += ps;
;     const bf16x8 pf = mk8((u32x4){pk2(pv[0], pv[1]), pk2(pv[2], pv[3]), pk2(pv[4], pv[5]), pk2(pv[6], pv[7])});
; #pragma unroll
;     for (int dt = 0; dt < 4; ++dt) O[hh][dt] = MFMA16(f.v[dt], pf, O[hh][dt]);
;   }
.Lmy_fast_w1:
	s_waitcnt lgkmcnt(4)
	v_mfma_f32_16x16x32_bf16 v[182:185], v[132:135], v[8:11], v[218:221]
	v_mfma_f32_16x16x32_bf16 v[182:185], v[136:139], v[12:15], v[182:185]
	v_mfma_f32_16x16x32_bf16 v[186:189], v[140:143], v[8:11], v[222:225]
	v_mfma_f32_16x16x32_bf16 v[186:189], v[128:131], v[12:15], v[186:189]
	v_mfma_f32_16x16x32_bf16 v[190:193], v[132:135], v[16:19], v[218:221]
	v_mfma_f32_16x16x32_bf16 v[190:193], v[136:139], v[20:23], v[190:193]
	v_mfma_f32_16x16x32_bf16 v[194:197], v[140:143], v[16:19], v[222:225]
	v_mfma_f32_16x16x32_bf16 v[194:197], v[128:131], v[20:23], v[194:197]
	s_waitcnt lgkmcnt(0)
	s_nop 2
	v_pk_fma_f32 v[240:241], v[182:183], s[34:35], v[2:3] op_sel:[0,0,1] op_sel_hi:[1,0,1] neg_lo:[0,0,1] neg_hi:[0,0,1]
	v_pk_fma_f32 v[242:243], v[184:185], s[34:35], v[2:3] op_sel:[0,0,1] op_sel_hi:[1,0,1] neg_lo:[0,0,1] neg_hi:[0,0,1]
	v_pk_fma_f32 v[244:245], v[186:187], s[34:35], v[2:3] op_sel:[0,0,1] op_sel_hi:[1,0,1] neg_lo:[0,0,1] neg_hi:[0,0,1]
	v_pk_fma_f32 v[246:247], v[188:189], s[34:35], v[2:3] op_sel:[0,0,1] op_sel_hi:[1,0,1] neg_lo:[0,0,1] neg_hi:[0,0,1]
	v_exp_f32_e32 v240, v240
	v_exp_f32_e32 v241, v241
	v_mfma_f32_16x16x32_bf16 v[182:185], v[132:135], v[24:27], v[218:221]
	v_exp_f32_e32 v242, v242
	v_add_f32_e32 v205, 0, v240
	v_mfma_f32_16x16x32_bf16 v[182:185], v[136:139], v[28:31], v[182:185]
	v_exp_f32_e32 v243, v243
	v_add_f32_e32 v205, v241, v205
	v_mfma_f32_16x16x32_bf16 v[186:189], v[140:143], v[24:27], v[222:225]
	v_exp_f32_e32 v244, v244
	v_add_f32_e32 v205, v242, v205
	v_mfma_f32_16x16x32_bf16 v[186:189], v[128:131], v[28:31], v[186:189]
	v_exp_f32_e32 v245, v245
	v_add_f32_e32 v205, v243, v205
	v_exp_f32_e32 v246, v246
	v_add_f32_e32 v205, v244, v205
	v_exp_f32_e32 v247, v247
	v_add_f32_e32 v205, v245, v205
	v_cvt_pk_bf16_f32 v248, v240, v241
	v_add_f32_e32 v205, v246, v205
	v_cvt_pk_bf16_f32 v249, v242, v243
	v_cvt_pk_bf16_f32 v250, v244, v245
	v_add_f32_e32 v205, v247, v205
	v_cvt_pk_bf16_f32 v251, v246, v247
	v_add_f32_e32 v155, v155, v205
	v_pk_fma_f32 v[240:241], v[190:191], s[34:35], v[2:3] op_sel_hi:[1,0,0] neg_lo:[0,0,1] neg_hi:[0,0,1]
	v_pk_fma_f32 v[242:243], v[192:193], s[34:35], v[2:3] op_sel_hi:[1,0,0] neg_lo:[0,0,1] neg_hi:[0,0,1]
	v_pk_fma_f32 v[244:245], v[194:195], s[34:35], v[2:3] op_sel_hi:[1,0,0] neg_lo:[0,0,1] neg_hi:[0,0,1]
	v_pk_fma_f32 v[246:247], v[196:197], s[34:35], v[2:3] op_sel_hi:[1,0,0] neg_lo:[0,0,1] neg_hi:[0,0,1]
	v_exp_f32_e32 v240, v240
	v_exp_f32_e32 v241, v241
	v_mfma_f32_16x16x32_bf16 v[190:193], v[132:135], v[32:35], v[218:221]
	v_exp_f32_e32 v242, v242
	v_add_f32_e32 v205, 0, v240
	v_mfma_f32_16x16x32_bf16 v[190:193], v[136:139], v[36:39], v[190:193]
	v_exp_f32_e32 v243, v243
	v_add_f32_e32 v205, v241, v205
	v_mfma_f32_16x16x32_bf16 v[194:197], v[140:143], v[32:35], v[222:225]
	v_exp_f32_e32 v244, v244
	v_add_f32_e32 v205, v242, v205
	v_mfma_f32_16x16x32_bf16 v[194:197], v[128:131], v[36:39], v[194:197]
	v_exp_f32_e32 v245, v245
	v_add_f32_e32 v205, v243, v205
	v_mfma_f32_16x16x32_bf16 v[100:103], v[124:127], v[248:251], v[100:103]
	v_exp_f32_e32 v246, v246
	v_add_f32_e32 v205, v244, v205
	v_mfma_f32_16x16x32_bf16 v[96:99], v[120:123], v[248:251], v[96:99]
	v_exp_f32_e32 v247, v247
	v_add_f32_e32 v205, v245, v205
	v_mfma_f32_16x16x32_bf16 v[92:95], v[116:119], v[248:251], v[92:95]
	v_cvt_pk_bf16_f32 v198, v240, v241
	v_add_f32_e32 v205, v246, v205
	v_mfma_f32_16x16x32_bf16 v[88:91], v[112:115], v[248:251], v[88:91]
	v_cvt_pk_bf16_f32 v199, v242, v243
	v_cvt_pk_bf16_f32 v200, v244, v245
	v_add_f32_e32 v205, v247, v205
	v_cvt_pk_bf16_f32 v201, v246, v247
	v_add_f32_e32 v154, v154, v205
	v_pk_fma_f32 v[240:241], v[182:183], s[34:35], v[0:1] op_sel_hi:[1,0,0] neg_lo:[0,0,1] neg_hi:[0,0,1]
	v_pk_fma_f32 v[242:243], v[184:185], s[34:35], v[0:1] op_sel_hi:[1,0,0] neg_lo:[0,0,1] neg_hi:[0,0,1]
	v_pk_fma_f32 v[244:245], v[186:187], s[34:35], v[0:1] op_sel_hi:[1,0,0] neg_lo:[0,0,1] neg_hi:[0,0,1]
	v_pk_fma_f32 v[246:247], v[188:189], s[34:35], v[0:1] op_sel_hi:[1,0,0] neg_lo:[0,0,1] neg_hi:[0,0,1]
	v_exp_f32_e32 v240, v240
	v_exp_f32_e32 v241, v241
	v_mfma_f32_16x16x32_bf16 v[84:87], v[124:127], v[198:201], v[84:87]
	v_exp_f32_e32 v242, v242
	v_add_f32_e32 v205, 0, v240
	v_mfma_f32_16x16x32_bf16 v[80:83], v[120:123], v[198:201], v[80:83]
	v_exp_f32_e32 v243, v243
	v_add_f32_e32 v205, v241, v205
	v_mfma_f32_16x16x32_bf16 v[76:79], v[116:119], v[198:201], v[76:79]
	v_exp_f32_e32 v244, v244
	v_add_f32_e32 v205, v242, v205
	v_mfma_f32_16x16x32_bf16 v[72:75], v[112:115], v[198:201], v[72:75]
	v_exp_f32_e32 v245, v245
	v_add_f32_e32 v205, v243, v205
	v_exp_f32_e32 v246, v246
	v_add_f32_e32 v205, v244, v205
	v_exp_f32_e32 v247, v247
	v_add_f32_e32 v205, v245, v205
	v_cvt_pk_bf16_f32 v248, v240, v241
	v_add_f32_e32 v205, v246, v205
	v_cvt_pk_bf16_f32 v249, v242, v243
	v_cvt_pk_bf16_f32 v250, v244, v245
	v_add_f32_e32 v205, v247, v205
	v_cvt_pk_bf16_f32 v251, v246, v247
	v_add_f32_e32 v153, v153, v205
	v_pk_fma_f32 v[240:241], v[190:191], s[34:35], v[178:179] op_sel:[0,0,1] op_sel_hi:[1,0,1] neg_lo:[0,0,1] neg_hi:[0,0,1]
	v_pk_fma_f32 v[242:243], v[192:193], s[34:35], v[178:179] op_sel:[0,0,1] op_sel_hi:[1,0,1] neg_lo:[0,0,1] neg_hi:[0,0,1]
	v_pk_fma_f32 v[244:245], v[194:195], s[34:35], v[178:179] op_sel:[0,0,1] op_sel_hi:[1,0,1] neg_lo:[0,0,1] neg_hi:[0,0,1]
	v_pk_fma_f32 v[246:247], v[196:197], s[34:35], v[178:179] op_sel:[0,0,1] op_sel_hi:[1,0,1] neg_lo:[0,0,1] neg_hi:[0,0,1]
	v_exp_f32_e32 v240, v240
	v_exp_f32_e32 v241, v241
	v_mfma_f32_16x16x32_bf16 v[68:71], v[124:127], v[248:251], v[68:71]
	v_exp_f32_e32 v242, v242
	v_add_f32_e32 v205, 0, v240
	v_mfma_f32_16x16x32_bf16 v[64:67], v[120:123], v[248:251], v[64:67]
	v_exp_f32_e32 v243, v243
	v_add_f32_e32 v205, v241, v205
	v_mfma_f32_16x16x32_bf16 v[60:63], v[116:119], v[248:251], v[60:63]
	v_exp_f32_e32 v244, v244
	v_add_f32_e32 v205, v242, v205
	v_mfma_f32_16x16x32_bf16 v[56:59], v[112:115], v[248:251], v[56:59]
	v_exp_f32_e32 v245, v245
	v_add_f32_e32 v205, v243, v205
	v_exp_f32_e32 v246, v246
	v_add_f32_e32 v205, v244, v205
	v_exp_f32_e32 v247, v247
	v_add_f32_e32 v205, v245, v205
	v_cvt_pk_bf16_f32 v198, v240, v241
	v_add_f32_e32 v205, v246, v205
	v_cvt_pk_bf16_f32 v199, v242, v243
	v_cvt_pk_bf16_f32 v200, v244, v245
	v_add_f32_e32 v205, v247, v205
	v_cvt_pk_bf16_f32 v201, v246, v247
	v_add_f32_e32 v152, v152, v205
	s_nop 0
	v_mfma_f32_16x16x32_bf16 v[52:55], v[124:127], v[198:201], v[52:55]
	v_mfma_f32_16x16x32_bf16 v[48:51], v[120:123], v[198:201], v[48:51]
	v_mfma_f32_16x16x32_bf16 v[44:47], v[116:119], v[198:201], v[44:47]
	v_mfma_f32_16x16x32_bf16 v[40:43], v[112:115], v[198:201], v[40:43]
	s_branch .LBB0_767
; #define MFMA16(a, b, c) __builtin_amdgcn_mfma_f32_16x16x32_bf16((a), (b), (c), 0, 0, 0)
; DI unsigned pk2(float lo, float hi) { f32x2 v = {lo, hi}; bf16x2_t b = __builtin_convertvector(v, bf16x2_t); return __builtin_bit_cast(unsigned, b); }
; template <int MODE>
; DI void nsa_chunk(const KVFrag& f, int kb, int t, bool selbit, const bf16x8 (&qf)[4][2], f32x4 (&O)[4][4], float (&m)[4], float (&l)[4], int quad, bool online) {
;     ...
;   for (int hh = 0; hh < 4; ++hh) {
;     f32x4 s[2];
; #pragma unroll
;     for (int a = 0; a < 2; ++a) { s[a] = MFMA16(f.k[a][0], qf[hh][0], ((f32x4){0.f, 0.f, 0.f, 0.f})); s[a] = MFMA16(f.k[a][1], qf[hh][1], s[a]); }
;     float mn = m[hh];
;     if (online) {
;       float cm = -1e30f;
; #pragma unroll
;       for (int idx = 0; idx < 8; ++idx) if (val[idx]) cm = fmaxf(cm, s[idx >> 2][idx & 3] * SC);
;       cm = fmaxf(cm, __shfl_xor(cm, 16)); cm = fmaxf(cm, __shfl_xor(cm, 32));
;       mn = fmaxf(mn, cm);
;       const float alpha = __builtin_amdgcn_exp2f(m[hh] - mn);
;       m[hh] = mn; l[hh] *= alpha;
; #pragma unroll
;       for (int dt = 0; dt < 4; ++dt) O[hh][dt] = O[hh][dt] * alpha;
;     }
;     float pv[8]; float ps = 0.f;
; #pragma unroll
;     for (int idx = 0; idx < 8; ++idx) { pv[idx] = val[idx] ? __builtin_amdgcn_exp2f(fmaf(s[idx >> 2][idx & 3], SC, -mn)) : 0.f; ps += pv[idx]; }
;     l[hh] += ps;
;     const bf16x8 pf = mk8((u32x4){pk2(pv[0], pv[1]), pk2(pv[2], pv[3]), pk2(pv[4], pv[5]), pk2(pv[6], pv[7])});
; #pragma unroll
;     for (int dt = 0; dt < 4; ++dt) O[hh][dt] = MFMA16(f.v[dt], pf, O[hh][dt]);
;   }
.Lmy_full_w1:
	s_waitcnt lgkmcnt(4)
	v_mfma_f32_16x16x32_bf16 v[182:185], v[132:135], v[8:11], 0
	v_mfma_f32_16x16x32_bf16 v[182:185], v[136:139], v[12:15], v[182:185]
	v_mfma_f32_16x16x32_bf16 v[186:189], v[140:143], v[8:11], 0
	v_mfma_f32_16x16x32_bf16 v[186:189], v[128:131], v[12:15], v[186:189]
	v_mfma_f32_16x16x32_bf16 v[190:193], v[132:135], v[16:19], 0
	v_mfma_f32_16x16x32_bf16 v[190:193], v[136:139], v[20:23], v[190:193]
	v_mfma_f32_16x16x32_bf16 v[194:197], v[140:143], v[16:19], 0
	v_mfma_f32_16x16x32_bf16 v[194:197], v[128:131], v[20:23], v[194:197]
	s_waitcnt lgkmcnt(0)
	s_nop 2
	v_pk_fma_f32 v[240:241], v[182:183], s[34:35], v[2:3] op_sel:[0,0,1] op_sel_hi:[1,0,1] neg_lo:[0,0,1] neg_hi:[0,0,1]
	v_pk_fma_f32 v[242:243], v[184:185], s[34:35], v[2:3] op_sel:[0,0,1] op_sel_hi:[1,0,1] neg_lo:[0,0,1] neg_hi:[0,0,1]
	v_pk_fma_f32 v[244:245], v[186:187], s[34:35], v[2:3] op_sel:[0,0,1] op_sel_hi:[1,0,1] neg_lo:[0,0,1] neg_hi:[0,0,1]
	v_pk_fma_f32 v[246:247], v[188:189], s[34:35], v[2:3] op_sel:[0,0,1] op_sel_hi:[1,0,1] neg_lo:[0,0,1] neg_hi:[0,0,1]
	v_exp_f32_e32 v240, v240
	v_exp_f32_e32 v241, v241
	v_mfma_f32_16x16x32_bf16 v[182:185], v[132:135], v[24:27], 0
	v_exp_f32_e32 v242, v242
	v_add_f32_e32 v205, 0, v240
	v_mfma_f32_16x16x32_bf16 v[182:185], v[136:139], v[28:31], v[182:185]
	v_exp_f32_e32 v243, v243
	v_add_f32_e32 v205, v241, v205
	v_mfma_f32_16x16x32_bf16 v[186:189], v[140:143], v[24:27], 0
	v_exp_f32_e32 v244, v244
	v_add_f32_e32 v205, v242, v205
	v_mfma_f32_16x16x32_bf16 v[186:189], v[128:131], v[28:31], v[186:189]
	v_exp_f32_e32 v245, v245
	v_add_f32_e32 v205, v243, v205
	v_exp_f32_e32 v246, v246
	v_add_f32_e32 v205, v244, v205
	v_exp_f32_e32 v247, v247
	v_add_f32_e32 v205, v245, v205
	v_cvt_pk_bf16_f32 v248, v240, v241
	v_add_f32_e32 v205, v246, v205
	v_cvt_pk_bf16_f32 v249, v242, v243
	v_cvt_pk_bf16_f32 v250, v244, v245
	v_add_f32_e32 v205, v247, v205
	v_cvt_pk_bf16_f32 v251, v246, v247
	v_add_f32_e32 v155, v155, v205
	v_pk_fma_f32 v[240:241], v[190:191], s[34:35], v[2:3] op_sel_hi:[1,0,0] neg_lo:[0,0,1] neg_hi:[0,0,1]
	v_pk_fma_f32 v[242:243], v[192:193], s[34:35], v[2:3] op_sel_hi:[1,0,0] neg_lo:[0,0,1] neg_hi:[0,0,1]
	v_pk_fma_f32 v[244:245], v[194:195], s[34:35], v[2:3] op_sel_hi:[1,0,0] neg_lo:[0,0,1] neg_hi:[0,0,1]
	v_pk_fma_f32 v[246:247], v[196:197], s[34:35], v[2:3] op_sel_hi:[1,0,0] neg_lo:[0,0,1] neg_hi:[0,0,1]
	v_exp_f32_e32 v240, v240
	v_exp_f32_e32 v241, v241
	v_mfma_f32_16x16x32_bf16 v[190:193], v[132:135], v[32:35], 0
	v_exp_f32_e32 v242, v242
	v_add_f32_e32 v205, 0, v240
	v_mfma_f32_16x16x32_bf16 v[190:193], v[136:139], v[36:39], v[190:193]
	v_exp_f32_e32 v243, v243
	v_add_f32_e32 v205, v241, v205
	v_mfma_f32_16x16x32_bf16 v[194:197], v[140:143], v[32:35], 0
	v_exp_f32_e32 v244, v244
	v_add_f32_e32 v205, v242, v205
	v_mfma_f32_16x16x32_bf16 v[194:197], v[128:131], v[36:39], v[194:197]
	v_exp_f32_e32 v245, v245
	v_add_f32_e32 v205, v243, v205
	v_mfma_f32_16x16x32_bf16 v[100:103], v[124:127], v[248:251], v[100:103]
	v_exp_f32_e32 v246, v246
	v_add_f32_e32 v205, v244, v205
	v_mfma_f32_16x16x32_bf16 v[96:99], v[120:123], v[248:251], v[96:99]
	v_exp_f32_e32 v247, v247
	v_add_f32_e32 v205, v245, v205
	v_mfma_f32_16x16x32_bf16 v[92:95], v[116:119], v[248:251], v[92:95]
	v_cvt_pk_bf16_f32 v198, v240, v241
	v_add_f32_e32 v205, v246, v205
	v_mfma_f32_16x16x32_bf16 v[88:91], v[112:115], v[248:251], v[88:91]
	v_cvt_pk_bf16_f32 v199, v242, v243
	v_cvt_pk_bf16_f32 v200, v244, v245
	v_add_f32_e32 v205, v247, v205
	v_cvt_pk_bf16_f32 v201, v246, v247
	v_add_f32_e32 v154, v154, v205
	v_pk_fma_f32 v[240:241], v[182:183], s[34:35], v[0:1] op_sel_hi:[1,0,0] neg_lo:[0,0,1] neg_hi:[0,0,1]
	v_pk_fma_f32 v[242:243], v[184:185], s[34:35], v[0:1] op_sel_hi:[1,0,0] neg_lo:[0,0,1] neg_hi:[0,0,1]
	v_pk_fma_f32 v[244:245], v[186:187], s[34:35], v[0:1] op_sel_hi:[1,0,0] neg_lo:[0,0,1] neg_hi:[0,0,1]
	v_pk_fma_f32 v[246:247], v[188:189], s[34:35], v[0:1] op_sel_hi:[1,0,0] neg_lo:[0,0,1] neg_hi:[0,0,1]
	v_exp_f32_e32 v240, v240
	v_exp_f32_e32 v241, v241
	v_mfma_f32_16x16x32_bf16 v[84:87], v[124:127], v[198:201], v[84:87]
	v_exp_f32_e32 v242, v242
	v_add_f32_e32 v205, 0, v240
	v_mfma_f32_16x16x32_bf16 v[80:83], v[120:123], v[198:201], v[80:83]
	v_exp_f32_e32 v243, v243
	v_add_f32_e32 v205, v241, v205
	v_mfma_f32_16x16x32_bf16 v[76:79], v[116:119], v[198:201], v[76:79]
	v_exp_f32_e32 v244, v244
	v_add_f32_e32 v205, v242, v205
	v_mfma_f32_16x16x32_bf16 v[72:75], v[112:115], v[198:201], v[72:75]
	v_exp_f32_e32 v245, v245
	v_add_f32_e32 v205, v243, v205
	v_exp_f32_e32 v246, v246
	v_add_f32_e32 v205, v244, v205
	v_exp_f32_e32 v247, v247
	v_add_f32_e32 v205, v245, v205
	v_cvt_pk_bf16_f32 v248, v240, v241
	v_add_f32_e32 v205, v246, v205
	v_cvt_pk_bf16_f32 v249, v242, v243
	v_cvt_pk_bf16_f32 v250, v244, v245
	v_add_f32_e32 v205, v247, v205
	v_cvt_pk_bf16_f32 v251, v246, v247
	v_add_f32_e32 v153, v153, v205
	v_pk_fma_f32 v[240:241], v[190:191], s[34:35], v[178:179] op_sel:[0,0,1] op_sel_hi:[1,0,1] neg_lo:[0,0,1] neg_hi:[0,0,1]
	v_pk_fma_f32 v[242:243], v[192:193], s[34:35], v[178:179] op_sel:[0,0,1] op_sel_hi:[1,0,1] neg_lo:[0,0,1] neg_hi:[0,0,1]
	v_pk_fma_f32 v[244:245], v[194:195], s[34:35], v[178:179] op_sel:[0,0,1] op_sel_hi:[1,0,1] neg_lo:[0,0,1] neg_hi:[0,0,1]
	v_pk_fma_f32 v[246:247], v[196:197], s[34:35], v[178:179] op_sel:[0,0,1] op_sel_hi:[1,0,1] neg_lo:[0,0,1] neg_hi:[0,0,1]
	v_exp_f32_e32 v240, v240
	v_exp_f32_e32 v241, v241
	v_mfma_f32_16x16x32_bf16 v[68:71], v[124:127], v[248:251], v[68:71]
	v_exp_f32_e32 v242, v242
	v_add_f32_e32 v205, 0, v240
	v_mfma_f32_16x16x32_bf16 v[64:67], v[120:123], v[248:251], v[64:67]
	v_exp_f32_e32 v243, v243
	v_add_f32_e32 v205, v241, v205
	v_mfma_f32_16x16x32_bf16 v[60:63], v[116:119], v[248:251], v[60:63]
	v_exp_f32_e32 v244, v244
	v_add_f32_e32 v205, v242, v205
	v_mfma_f32_16x16x32_bf16 v[56:59], v[112:115], v[248:251], v[56:59]
	v_exp_f32_e32 v245, v245
	v_add_f32_e32 v205, v243, v205
	v_exp_f32_e32 v246, v246
	v_add_f32_e32 v205, v244, v205
	v_exp_f32_e32 v247, v247
	v_add_f32_e32 v205, v245, v205
	v_cvt_pk_bf16_f32 v198, v240, v241
	v_add_f32_e32 v205, v246, v205
	v_cvt_pk_bf16_f32 v199, v242, v243
	v_cvt_pk_bf16_f32 v200, v244, v245
	v_add_f32_e32 v205, v247, v205
	v_cvt_pk_bf16_f32 v201, v246, v247
	v_add_f32_e32 v152, v152, v205
	s_nop 0
	v_mfma_f32_16x16x32_bf16 v[52:55], v[124:127], v[198:201], v[52:55]
	v_mfma_f32_16x16x32_bf16 v[48:51], v[120:123], v[198:201], v[48:51]
	v_mfma_f32_16x16x32_bf16 v[44:47], v[116:119], v[198:201], v[44:47]
	v_mfma_f32_16x16x32_bf16 v[40:43], v[112:115], v[198:201], v[40:43]
	s_branch .LBB0_767
